# o16 + 1536 regular w_in conversion items [0x3b00,0x4100) deferred to GU1 idle workgroups (tail-mode re-entry of the prologue loop); small items stay in the prologue
# baseline (speedup 1.0000x reference)
.Lpro_t0:
	v_or_b32_e32 v171, 0xfffdf800, v132
	v_lshlrev_b32_e32 v154, 1, v6
	v_lshlrev_b32_e32 v156, 1, v8
	v_lshlrev_b32_e32 v158, 1, v10
	v_lshlrev_b32_e32 v160, 1, v12
	s_mov_b32 s46, 0x10000
	s_movk_i32 s47, 0x2000
	s_mov_b32 s69, 0x16000
	s_movk_i32 s70, 0x5000
	s_movk_i32 s71, 0xb0
	s_movk_i32 s72, 0xff80
	s_movk_i32 s73, 0x5800
	s_mov_b32 s74, 0xb000
	v_mbcnt_hi_u32_b32 v172, -1, v202
	v_mov_b32_e32 v173, 63
	v_mov_b32_e32 v174, 6
	v_mov_b32_e32 v175, 39
	v_mov_b32_e32 v176, v130
	s_mov_b32 s75, 0x1b000
	s_mov_b32 s76, 0x21000
	s_mov_b32 s77, 0x26000
	s_mov_b32 s78, 0x2c000
	s_mov_b32 s79, 0x31000
	s_mov_b32 s88, 0x37000
	s_mov_b32 s89, 0x3c000
	s_mov_b32 s90, 0x42000
	s_mov_b32 s91, 0x47000
	s_mov_b32 s92, 0x4d000
	s_mov_b32 s64, 0x52000
	s_movk_i32 s65, 0x41ff
	s_cmp_eq_u32 s96, 0
	s_cbranch_scc1 .Lpro_t1
	s_movk_i32 s65, 0x40ff

.LBB0_7:
	s_or_b64 exec, exec, s[14:15]
	s_movk_i32 s93, 0x1600
	v_cmp_gt_i32_e64 s[94:95], s93, v176
	v_add_u32_e32 v176, s42, v176
	v_cmp_le_i32_e64 s[66:67], s93, v176
	v_mov_b32_e32 v177, 0xb00
	s_and_b64 vcc, s[94:95], s[66:67]
	s_nop 1
	v_cndmask_b32_e32 v177, 0, v177, vcc
	v_add_u32_e32 v176, v176, v177
	v_lshl_add_u32 v170, v177, 3, v170
	s_movk_i32 s93, 0x3b00
	v_sub_u32_e32 v177, v176, v177
	v_subrev_u32_e32 v177, s42, v177
	v_cmp_gt_i32_e64 s[94:95], s93, v177
	v_cmp_le_i32_e64 s[66:67], s93, v176
	v_mov_b32_e32 v177, 0x600
	s_and_b64 vcc, s[94:95], s[66:67]
	s_nop 1
	v_cndmask_b32_e32 v177, 0, v177, vcc
	v_add_u32_e32 v176, v176, v177
	v_lshl_add_u32 v170, v177, 3, v170
	v_cmp_lt_i32_e32 vcc, s65, v176
	s_or_b64 s[34:35], vcc, s[34:35]
	v_add_u32_e32 v170, s33, v170
	s_andn2_b64 exec, exec, s[34:35]
	s_cbranch_execz .LBB0_115

.Lwt_any:
	s_lshl_b32 s3, s3, 3
	s_add_u32 s3, s3, 0x3b00
	v_mov_b32_e32 v139, v0
	v_ashrrev_i32_e32 v2, 6, v139
	v_and_b32_e32 v131, 63, v139
	v_and_b32_e32 v133, 15, v139
	v_add_u32_e32 v130, s3, v2
	s_add_u32 s20, s86, 0x4360200
	s_addc_u32 s21, s87, 0
	s_mov_b64 s[24:25], exec
	s_branch .Lpro_body
